# stack plus counted vmcnt waits per arithmetic piece for the merge gate loads (batch 0) instead of one vmcnt(0)
# speedup vs baseline: 1.0050x; 1.0041x over previous
; __device__ __forceinline__ void scale_acc_by_gate_ratio(f32x4 (&acc)[2][2][4][2], const bf16_t* ga_base, bool single, const Unit& u, int wr, int wc, int fr, int fq) {
;     const size_t row0 = (size_t)(u.pm * BM + wr * 64 + fr); const int col0 = u.pn * BM + wc * 32 + 8 * fq;
;     const bf16_t* gp = ga_base + row0 * 3072 + col0;
;     ...
; #pragma unroll
;     for (int bt = 0; bt < 2; ++bt) {
;         u32x4 X[8], Y[8];
; #pragma unroll
;         for (int m = 0; m < 4; ++m)
; #pragma unroll
;             for (int bj = 0; bj < 2; ++bj) {
;                 const bf16_t* p0 = gp + (size_t)(m * 16) * 3072 + bj * HALF; const bf16_t* p1 = p0 + (size_t)HALF * 3072;
;                 const bf16_t* px = bt == 0 ? p0 : GSEL(single, p0, p1);
;                 const bf16_t* py = bt == 0 ? GSEL(single, p1, p0 + 1024) : GSEL(single, p0, p1 + 1024);
;                 X[m * 2 + bj] = *(const u32x4*)px; Y[m * 2 + bj] = *(const u32x4*)py;
;             }
;         __builtin_amdgcn_sched_barrier(0);
; #pragma unroll
;         for (int m = 0; m < 4; ++m)
; #pragma unroll
;             for (int bj = 0; bj < 2; ++bj) {
;                 const u32x4 gx = X[m * 2 + bj], gy = Y[m * 2 + bj];
;                 const unsigned xw[4] = {gx.x, gx.y, gx.z, gx.w}, yw[4] = {gy.x, gy.y, gy.z, gy.w};
; #pragma unroll
;                 for (int w = 0; w < 4; ++w) {
;                     const float x_ = bf_lo(xw[w]), x2_ = bf_hi(xw[w]), y_ = bf_lo(yw[w]), y2_ = bf_hi(yw[w]);
;                     const float q_ = x_ * __builtin_amdgcn_rcpf(y_), q2_ = x2_ * __builtin_amdgcn_rcpf(y2_);
;                     const int n = w >> 1, e = (w & 1) * 2;
;                     if (bt == 0) {
;                         acc[0][bj][m][n][e] *= GSEL(single, x_, q_); acc[0][bj][m][n][e + 1] *= GSEL(single, x2_, q2_);
;                         acc[1][bj][m][n][e] *= GSEL(single, y_, 1.0f); acc[1][bj][m][n][e + 1] *= GSEL(single, y2_, 1.0f);
.LBB0_47:
	s_and_b32 s13, s42, 63
	s_add_i32 s13, s13, -6
	s_lshl_b32 s6, s13, 10
	s_ashr_i32 s7, s6, 31
	s_lshl_b64 s[6:7], s[6:7], 1
	v_readlane_b32 s26, v253, 24
	v_readlane_b32 s27, v253, 25
	s_add_u32 s6, s26, s6
	s_addc_u32 s7, s27, s7
	s_cmp_eq_u32 s13, 1
	s_cselect_b64 vcc, -1, 0
	s_lshl_b32 s26, s43, 8
	v_lshl_add_u32 v192, s46, 8, v233
	v_or_b32_e32 v128, s26, v188
	v_mov_b64_e32 v[130:131], s[6:7]
	v_mad_i64_i32 v[130:131], s[6:7], v192, s33, v[130:131]
	v_ashrrev_i32_e32 v129, 31, v128
	v_lshl_add_u64 v[194:195], v[128:129], 1, v[130:131]
	s_mov_b64 s[6:7], 0xc0000
	v_lshl_add_u64 v[196:197], v[194:195], 0, s[6:7]
	s_mov_b64 s[6:7], 0x800
	v_lshl_add_u64 v[128:129], v[194:195], 0, s[6:7]
	s_mov_b64 s[6:7], 0xc0100
	v_cndmask_b32_e32 v129, v197, v129, vcc
	v_cndmask_b32_e32 v128, v196, v128, vcc
	v_lshl_add_u64 v[198:199], v[194:195], 0, s[6:7]
	s_mov_b64 s[6:7], 0x900
	global_load_dwordx4 v[238:241], v[128:129], off
	v_lshl_add_u64 v[128:129], v[194:195], 0, s[6:7]
	s_mov_b64 s[6:7], 0xd8000
	v_cndmask_b32_e32 v129, v199, v129, vcc
	v_cndmask_b32_e32 v128, v198, v128, vcc
	v_lshl_add_u64 v[200:201], v[194:195], 0, s[6:7]
	s_mov_b64 s[6:7], 0x18800
	global_load_dwordx4 v[242:245], v[194:195], off
	global_load_dwordx4 v[246:249], v[194:195], off offset:256
	global_load_dwordx4 v[180:183], v[128:129], off
	v_lshl_add_u64 v[128:129], v[194:195], 0, s[6:7]
	s_mov_b32 s6, 0x18000
	v_add_co_u32_e64 v130, s[6:7], s6, v194
	v_cndmask_b32_e32 v129, v201, v129, vcc
	s_nop 0
	v_addc_co_u32_e64 v131, s[6:7], 0, v195, s[6:7]
	s_mov_b64 s[6:7], 0xd8100
	v_cndmask_b32_e32 v128, v200, v128, vcc
	v_lshl_add_u64 v[202:203], v[194:195], 0, s[6:7]
	s_mov_b64 s[6:7], 0x18900
	global_load_dwordx4 v[168:171], v[128:129], off
	v_lshl_add_u64 v[128:129], v[194:195], 0, s[6:7]
	s_mov_b64 s[6:7], 0xf0000
	v_cndmask_b32_e32 v129, v203, v129, vcc
	v_cndmask_b32_e32 v128, v202, v128, vcc
	v_lshl_add_u64 v[204:205], v[194:195], 0, s[6:7]
	s_mov_b64 s[6:7], 0x30800
	global_load_dwordx4 v[172:175], v[130:131], off
	global_load_dwordx4 v[160:163], v[130:131], off offset:256
	global_load_dwordx4 v[164:167], v[128:129], off
	v_lshl_add_u64 v[128:129], v[194:195], 0, s[6:7]
	s_mov_b32 s6, 0x30000
	v_add_co_u32_e64 v130, s[6:7], s6, v194
	v_cndmask_b32_e32 v129, v205, v129, vcc
	s_nop 0
	v_addc_co_u32_e64 v131, s[6:7], 0, v195, s[6:7]
	s_mov_b64 s[6:7], 0xf0100
	v_cndmask_b32_e32 v128, v204, v128, vcc
	v_lshl_add_u64 v[206:207], v[194:195], 0, s[6:7]
	s_mov_b64 s[6:7], 0x30900
	global_load_dwordx4 v[152:155], v[128:129], off
	v_lshl_add_u64 v[128:129], v[194:195], 0, s[6:7]
	s_mov_b64 s[6:7], 0x108000
	v_cndmask_b32_e32 v129, v207, v129, vcc
	v_cndmask_b32_e32 v128, v206, v128, vcc
	v_lshl_add_u64 v[208:209], v[194:195], 0, s[6:7]
	s_mov_b64 s[6:7], 0x48800
	global_load_dwordx4 v[156:159], v[130:131], off
	global_load_dwordx4 v[144:147], v[130:131], off offset:256
	global_load_dwordx4 v[148:151], v[128:129], off
	v_lshl_add_u64 v[128:129], v[194:195], 0, s[6:7]
	v_add_co_u32_e64 v130, s[6:7], s83, v194
	v_cndmask_b32_e32 v129, v209, v129, vcc
	s_nop 0
	v_addc_co_u32_e64 v131, s[6:7], 0, v195, s[6:7]
	s_mov_b64 s[6:7], 0x108100
	v_cndmask_b32_e32 v128, v208, v128, vcc
	v_lshl_add_u64 v[210:211], v[194:195], 0, s[6:7]
	s_mov_b64 s[6:7], 0x48900
	global_load_dwordx4 v[136:139], v[128:129], off
	v_lshl_add_u64 v[128:129], v[194:195], 0, s[6:7]
	v_cndmask_b32_e32 v133, v211, v129, vcc
	v_cndmask_b32_e32 v132, v210, v128, vcc
	global_load_dwordx4 v[140:143], v[130:131], off
	s_nop 0
	global_load_dwordx4 v[128:131], v[130:131], off offset:256
	s_nop 0
	global_load_dwordx4 v[132:135], v[132:133], off
	s_and_b64 s[6:7], vcc, exec
	s_mov_b64 s[6:7], 0x100
	v_lshl_add_u64 v[224:225], v[194:195], 0, s[6:7]
	s_mov_b64 s[6:7], 0x18000
	v_lshl_add_u64 v[222:223], v[194:195], 0, s[6:7]
	s_mov_b64 s[6:7], 0x18100
	v_lshl_add_u64 v[220:221], v[194:195], 0, s[6:7]
	s_mov_b64 s[6:7], 0x30000
	v_lshl_add_u64 v[218:219], v[194:195], 0, s[6:7]
	s_mov_b64 s[6:7], 0x30100
	v_lshl_add_u64 v[216:217], v[194:195], 0, s[6:7]
	s_mov_b64 s[6:7], 0x48000
	v_lshl_add_u64 v[214:215], v[194:195], 0, s[6:7]
	s_mov_b64 s[6:7], 0x48100
	s_cselect_b32 s94, 0xc0800, 0
	v_lshl_add_u64 v[212:213], v[194:195], 0, s[6:7]
	s_waitcnt vmcnt(14)
	v_and_b32_e32 v178, 0xffff0000, v238
	v_rcp_f32_e32 v193, v178
	v_lshlrev_b32_e32 v237, 16, v238
	v_and_b32_e32 v252, 0xffff0000, v242
	v_rcp_f32_e32 v238, v237
	v_mul_f32_e32 v193, v193, v252
	v_cndmask_b32_e32 v193, v252, v193, vcc
	v_cndmask_b32_e64 v178, v178, 1.0, vcc
	v_mul_f32_e32 v61, v61, v193
	v_cndmask_b32_e64 v193, v237, 1.0, vcc
	v_mul_f32_e32 v125, v125, v178
	v_and_b32_e32 v178, 0xffff0000, v239
	v_lshlrev_b32_e32 v242, 16, v242
	v_mul_f32_e32 v124, v124, v193
	v_rcp_f32_e32 v193, v178
	v_mul_f32_e32 v238, v238, v242
	v_cndmask_b32_e32 v238, v242, v238, vcc
	v_lshlrev_b32_e32 v237, 16, v239
	v_mul_f32_e32 v60, v60, v238
	v_rcp_f32_e32 v238, v237
	v_and_b32_e32 v239, 0xffff0000, v243
	v_mul_f32_e32 v193, v193, v239
	v_cndmask_b32_e32 v193, v239, v193, vcc
	v_cndmask_b32_e64 v178, v178, 1.0, vcc
	v_lshlrev_b32_e32 v242, 16, v243
	v_mul_f32_e32 v63, v63, v193
	v_cndmask_b32_e64 v193, v237, 1.0, vcc
	v_mul_f32_e32 v127, v127, v178
	v_and_b32_e32 v178, 0xffff0000, v240
	v_mul_f32_e32 v238, v238, v242
	v_mul_f32_e32 v126, v126, v193
	v_rcp_f32_e32 v193, v178
	v_cndmask_b32_e32 v238, v242, v238, vcc
	v_lshlrev_b32_e32 v237, 16, v240
	v_mul_f32_e32 v62, v62, v238
	v_rcp_f32_e32 v238, v237
	v_and_b32_e32 v239, 0xffff0000, v244
	v_mul_f32_e32 v193, v193, v239
	v_lshlrev_b32_e32 v240, 16, v244
	v_cndmask_b32_e32 v193, v239, v193, vcc
	v_cndmask_b32_e64 v178, v178, 1.0, vcc
	v_mul_f32_e32 v238, v238, v240
	v_mul_f32_e32 v57, v57, v193
	v_cndmask_b32_e64 v193, v237, 1.0, vcc
	v_mul_f32_e32 v121, v121, v178
	v_and_b32_e32 v178, 0xffff0000, v241
	v_cndmask_b32_e32 v238, v240, v238, vcc
	v_mul_f32_e32 v120, v120, v193
	v_rcp_f32_e32 v193, v178
	v_lshlrev_b32_e32 v237, 16, v241
	v_mul_f32_e32 v56, v56, v238
	v_rcp_f32_e32 v238, v237
	v_and_b32_e32 v239, 0xffff0000, v245
	v_mul_f32_e32 v193, v193, v239
	v_lshlrev_b32_e32 v240, 16, v245
	v_mul_f32_e32 v238, v238, v240
	v_cndmask_b32_e32 v193, v239, v193, vcc
	v_cndmask_b32_e32 v238, v240, v238, vcc
	v_mul_f32_e32 v59, v59, v193
	v_cndmask_b32_e64 v193, v237, 1.0, vcc
	v_cndmask_b32_e64 v178, v178, 1.0, vcc
	v_mul_f32_e32 v58, v58, v238
	v_mul_f32_e32 v122, v122, v193
	v_mul_f32_e32 v123, v123, v178
	s_waitcnt vmcnt(12)
; __device__ __forceinline__ void scale_acc_by_gate_ratio(f32x4 (&acc)[2][2][4][2], const bf16_t* ga_base, bool single, const Unit& u, int wr, int wc, int fr, int fq) {
;     ...
;         for (int m = 0; m < 4; ++m)
; #pragma unroll
;             for (int bj = 0; bj < 2; ++bj) {
;                 const u32x4 gx = X[m * 2 + bj], gy = Y[m * 2 + bj];
;                 const unsigned xw[4] = {gx.x, gx.y, gx.z, gx.w}, yw[4] = {gy.x, gy.y, gy.z, gy.w};
; #pragma unroll
;                 for (int w = 0; w < 4; ++w) {
;                     const float x_ = bf_lo(xw[w]), x2_ = bf_hi(xw[w]), y_ = bf_lo(yw[w]), y2_ = bf_hi(yw[w]);
;                     const float q_ = x_ * __builtin_amdgcn_rcpf(y_), q2_ = x2_ * __builtin_amdgcn_rcpf(y2_);
;                     const int n = w >> 1, e = (w & 1) * 2;
;                     if (bt == 0) {
;                         acc[0][bj][m][n][e] *= GSEL(single, x_, q_); acc[0][bj][m][n][e + 1] *= GSEL(single, x2_, q2_);
;                         acc[1][bj][m][n][e] *= GSEL(single, y_, 1.0f); acc[1][bj][m][n][e + 1] *= GSEL(single, y2_, 1.0f);
	v_and_b32_e32 v178, 0xffff0000, v180
	v_lshlrev_b32_e32 v180, 16, v180
	v_rcp_f32_e32 v237, v180
	v_rcp_f32_e32 v193, v178
	v_cndmask_b32_e64 v178, v178, 1.0, vcc
	v_cndmask_b32_e64 v180, v180, 1.0, vcc
	v_mul_f32_e32 v109, v109, v178
	v_and_b32_e32 v178, 0xffff0000, v181
	v_lshlrev_b32_e32 v239, 16, v246
	v_mul_f32_e32 v108, v108, v180
	v_rcp_f32_e32 v180, v178
	v_and_b32_e32 v238, 0xffff0000, v246
	v_mul_f32_e32 v237, v237, v239
	v_mul_f32_e32 v193, v193, v238
	v_cndmask_b32_e32 v237, v239, v237, vcc
	v_mul_f32_e32 v28, v28, v237
	v_cndmask_b32_e32 v193, v238, v193, vcc
	v_lshlrev_b32_e32 v181, 16, v181
	v_and_b32_e32 v237, 0xffff0000, v247
	v_mul_f32_e32 v29, v29, v193
	v_rcp_f32_e32 v193, v181
	v_mul_f32_e32 v180, v180, v237
	v_cndmask_b32_e32 v180, v237, v180, vcc
	v_cndmask_b32_e64 v178, v178, 1.0, vcc
	v_mul_f32_e32 v31, v31, v180
	v_cndmask_b32_e64 v180, v181, 1.0, vcc
	v_mul_f32_e32 v111, v111, v178
	v_and_b32_e32 v178, 0xffff0000, v182
	v_lshlrev_b32_e32 v238, 16, v247
	v_mul_f32_e32 v110, v110, v180
	v_rcp_f32_e32 v180, v178
	v_mul_f32_e32 v193, v193, v238
	v_lshlrev_b32_e32 v181, 16, v182
	v_cndmask_b32_e32 v193, v238, v193, vcc
	v_rcp_f32_e32 v182, v181
	v_mul_f32_e32 v30, v30, v193
	v_and_b32_e32 v193, 0xffff0000, v248
	v_mul_f32_e32 v180, v180, v193
	v_lshlrev_b32_e32 v237, 16, v248
	v_cndmask_b32_e32 v180, v193, v180, vcc
	v_cndmask_b32_e64 v178, v178, 1.0, vcc
	v_mul_f32_e32 v182, v182, v237
	v_mul_f32_e32 v25, v25, v180
	v_cndmask_b32_e64 v180, v181, 1.0, vcc
	v_mul_f32_e32 v101, v101, v178
	v_and_b32_e32 v178, 0xffff0000, v183
	v_cndmask_b32_e32 v182, v237, v182, vcc
	v_mul_f32_e32 v100, v100, v180
	v_rcp_f32_e32 v180, v178
	v_lshlrev_b32_e32 v181, 16, v183
	v_mul_f32_e32 v24, v24, v182
	v_rcp_f32_e32 v182, v181
	v_and_b32_e32 v183, 0xffff0000, v249
	v_mul_f32_e32 v180, v180, v183
	v_lshlrev_b32_e32 v193, 16, v249
	v_mul_f32_e32 v182, v182, v193
	v_cndmask_b32_e32 v180, v183, v180, vcc
	v_cndmask_b32_e32 v182, v193, v182, vcc
	v_mul_f32_e32 v27, v27, v180
	v_cndmask_b32_e64 v180, v181, 1.0, vcc
	v_cndmask_b32_e64 v178, v178, 1.0, vcc
	v_mul_f32_e32 v26, v26, v182
	v_mul_f32_e32 v102, v102, v180
	v_mul_f32_e32 v103, v103, v178
	s_waitcnt vmcnt(10)
	v_and_b32_e32 v178, 0xffff0000, v168
	v_lshlrev_b32_e32 v168, 16, v168
	v_rcp_f32_e32 v181, v168
	v_rcp_f32_e32 v180, v178
	v_and_b32_e32 v182, 0xffff0000, v172
	v_lshlrev_b32_e32 v172, 16, v172
	v_cndmask_b32_e64 v168, v168, 1.0, vcc
	v_mul_f32_e32 v181, v181, v172
	v_mul_f32_e32 v116, v116, v168
	v_cndmask_b32_e64 v168, v178, 1.0, vcc
	v_mul_f32_e32 v180, v180, v182
	v_cndmask_b32_e32 v172, v172, v181, vcc
	v_mul_f32_e32 v117, v117, v168
	v_and_b32_e32 v168, 0xffff0000, v169
	v_lshlrev_b32_e32 v169, 16, v169
	v_mul_f32_e32 v52, v52, v172
	v_cndmask_b32_e32 v172, v182, v180, vcc
	v_rcp_f32_e32 v178, v169
	v_mul_f32_e32 v53, v53, v172
	v_rcp_f32_e32 v172, v168
	v_cndmask_b32_e64 v168, v168, 1.0, vcc
	v_cndmask_b32_e64 v169, v169, 1.0, vcc
	v_mul_f32_e32 v119, v119, v168
	v_and_b32_e32 v168, 0xffff0000, v170
	v_and_b32_e32 v180, 0xffff0000, v173
	v_lshlrev_b32_e32 v173, 16, v173
	v_mul_f32_e32 v118, v118, v169
	v_rcp_f32_e32 v169, v168
	v_mul_f32_e32 v178, v178, v173
	v_mul_f32_e32 v172, v172, v180
	v_cndmask_b32_e32 v173, v173, v178, vcc
	v_mul_f32_e32 v54, v54, v173
	v_cndmask_b32_e32 v172, v180, v172, vcc
	v_lshlrev_b32_e32 v170, 16, v170
	v_and_b32_e32 v173, 0xffff0000, v174
	v_mul_f32_e32 v55, v55, v172
	v_rcp_f32_e32 v172, v170
	v_mul_f32_e32 v169, v169, v173
	v_cndmask_b32_e32 v169, v173, v169, vcc
	v_cndmask_b32_e64 v168, v168, 1.0, vcc
	v_mul_f32_e32 v49, v49, v169
	v_cndmask_b32_e64 v169, v170, 1.0, vcc
	v_mul_f32_e32 v113, v113, v168
	v_and_b32_e32 v168, 0xffff0000, v171
	v_lshlrev_b32_e32 v174, 16, v174
	v_mul_f32_e32 v112, v112, v169
	v_rcp_f32_e32 v169, v168
	v_lshlrev_b32_e32 v170, 16, v171
	v_mul_f32_e32 v172, v172, v174
	v_rcp_f32_e32 v171, v170
	v_cndmask_b32_e32 v172, v174, v172, vcc
	v_mul_f32_e32 v48, v48, v172
	v_and_b32_e32 v172, 0xffff0000, v175
	v_mul_f32_e32 v169, v169, v172
	v_lshlrev_b32_e32 v173, 16, v175
	v_mul_f32_e32 v171, v171, v173
	v_cndmask_b32_e32 v169, v172, v169, vcc
	v_cndmask_b32_e32 v171, v173, v171, vcc
	v_mul_f32_e32 v51, v51, v169
	v_cndmask_b32_e64 v169, v170, 1.0, vcc
	v_cndmask_b32_e64 v168, v168, 1.0, vcc
	v_mul_f32_e32 v50, v50, v171
	v_mul_f32_e32 v114, v114, v169
	v_mul_f32_e32 v115, v115, v168
	s_waitcnt vmcnt(8)
	v_and_b32_e32 v168, 0xffff0000, v164
	v_lshlrev_b32_e32 v164, 16, v164
	v_rcp_f32_e32 v170, v164
	v_rcp_f32_e32 v169, v168
	v_and_b32_e32 v171, 0xffff0000, v160
	v_lshlrev_b32_e32 v160, 16, v160
	v_mul_f32_e32 v170, v170, v160
	v_mul_f32_e32 v169, v169, v171
	v_cndmask_b32_e32 v160, v160, v170, vcc
	v_mul_f32_e32 v20, v20, v160
	v_cndmask_b32_e32 v160, v171, v169, vcc
	v_mul_f32_e32 v21, v21, v160
	v_cndmask_b32_e64 v160, v164, 1.0, vcc
	v_mul_f32_e32 v92, v92, v160
	v_cndmask_b32_e64 v160, v168, 1.0, vcc
	v_mul_f32_e32 v93, v93, v160
	v_and_b32_e32 v160, 0xffff0000, v165
	v_lshlrev_b32_e32 v165, 16, v165
	v_rcp_f32_e32 v168, v165
	v_rcp_f32_e32 v164, v160
	v_and_b32_e32 v169, 0xffff0000, v161
	v_lshlrev_b32_e32 v161, 16, v161
	v_mul_f32_e32 v168, v168, v161
	v_mul_f32_e32 v164, v164, v169
	v_cndmask_b32_e32 v161, v161, v168, vcc
	v_mul_f32_e32 v22, v22, v161
	v_cndmask_b32_e32 v161, v169, v164, vcc
	v_mul_f32_e32 v23, v23, v161
	v_cndmask_b32_e64 v161, v165, 1.0, vcc
	v_mul_f32_e32 v94, v94, v161
	v_cndmask_b32_e64 v160, v160, 1.0, vcc
	v_and_b32_e32 v161, 0xffff0000, v166
	v_mul_f32_e32 v95, v95, v160
	v_rcp_f32_e32 v160, v161
	v_lshlrev_b32_e32 v164, 16, v166
	v_rcp_f32_e32 v165, v164
	v_and_b32_e32 v166, 0xffff0000, v162
	v_mul_f32_e32 v160, v160, v166
	v_lshlrev_b32_e32 v162, 16, v162
	v_cndmask_b32_e32 v160, v166, v160, vcc
	v_mul_f32_e32 v165, v165, v162
	v_mul_f32_e32 v17, v17, v160
	v_cndmask_b32_e64 v160, v164, 1.0, vcc
	v_cndmask_b32_e32 v162, v162, v165, vcc
	v_mul_f32_e32 v160, v84, v160
	v_cndmask_b32_e64 v84, v161, 1.0, vcc
	v_mul_f32_e32 v16, v16, v162
	v_mul_f32_e32 v161, v85, v84
	v_and_b32_e32 v84, 0xffff0000, v167
	v_lshlrev_b32_e32 v162, 16, v167
	v_rcp_f32_e32 v85, v84
	v_rcp_f32_e32 v164, v162
	v_and_b32_e32 v165, 0xffff0000, v163
	v_lshlrev_b32_e32 v163, 16, v163
	v_mul_f32_e32 v85, v85, v165
	v_mul_f32_e32 v164, v164, v163
	v_cndmask_b32_e32 v163, v163, v164, vcc
	v_cndmask_b32_e32 v85, v165, v85, vcc
	v_mul_f32_e32 v18, v18, v163
	v_mul_f32_e32 v19, v19, v85
	v_cndmask_b32_e64 v85, v162, 1.0, vcc
	v_cndmask_b32_e64 v84, v84, 1.0, vcc
	v_mul_f32_e32 v162, v86, v85
	v_mul_f32_e32 v163, v87, v84
	s_waitcnt vmcnt(6)
; __device__ __forceinline__ void scale_acc_by_gate_ratio(f32x4 (&acc)[2][2][4][2], const bf16_t* ga_base, bool single, const Unit& u, int wr, int wc, int fr, int fq) {
;     ...
;         for (int m = 0; m < 4; ++m)
; #pragma unroll
;             for (int bj = 0; bj < 2; ++bj) {
;                 const u32x4 gx = X[m * 2 + bj], gy = Y[m * 2 + bj];
;                 const unsigned xw[4] = {gx.x, gx.y, gx.z, gx.w}, yw[4] = {gy.x, gy.y, gy.z, gy.w};
; #pragma unroll
;                 for (int w = 0; w < 4; ++w) {
;                     const float x_ = bf_lo(xw[w]), x2_ = bf_hi(xw[w]), y_ = bf_lo(yw[w]), y2_ = bf_hi(yw[w]);
;                     const float q_ = x_ * __builtin_amdgcn_rcpf(y_), q2_ = x2_ * __builtin_amdgcn_rcpf(y2_);
;                     const int n = w >> 1, e = (w & 1) * 2;
;                     if (bt == 0) {
;                         acc[0][bj][m][n][e] *= GSEL(single, x_, q_); acc[0][bj][m][n][e + 1] *= GSEL(single, x2_, q2_);
;                         acc[1][bj][m][n][e] *= GSEL(single, y_, 1.0f); acc[1][bj][m][n][e + 1] *= GSEL(single, y2_, 1.0f);
	v_and_b32_e32 v84, 0xffff0000, v152
	v_rcp_f32_e32 v85, v84
	v_lshlrev_b32_e32 v86, 16, v152
	v_rcp_f32_e32 v87, v86
	v_and_b32_e32 v152, 0xffff0000, v156
	v_mul_f32_e32 v85, v85, v152
	v_cndmask_b32_e32 v85, v152, v85, vcc
	v_cndmask_b32_e64 v84, v84, 1.0, vcc
	v_lshlrev_b32_e32 v156, 16, v156
	v_mul_f32_e32 v45, v45, v85
	v_cndmask_b32_e64 v85, v86, 1.0, vcc
	v_mul_f32_e32 v105, v105, v84
	v_and_b32_e32 v84, 0xffff0000, v153
	v_mul_f32_e32 v87, v87, v156
	v_mul_f32_e32 v104, v104, v85
	v_rcp_f32_e32 v85, v84
	v_cndmask_b32_e32 v87, v156, v87, vcc
	v_lshlrev_b32_e32 v86, 16, v153
	v_mul_f32_e32 v44, v44, v87
	v_rcp_f32_e32 v87, v86
	v_and_b32_e32 v152, 0xffff0000, v157
	v_mul_f32_e32 v85, v85, v152
	v_lshlrev_b32_e32 v153, 16, v157
	v_cndmask_b32_e32 v85, v152, v85, vcc
	v_cndmask_b32_e64 v84, v84, 1.0, vcc
	v_mul_f32_e32 v87, v87, v153
	v_mul_f32_e32 v47, v47, v85
	v_cndmask_b32_e64 v85, v86, 1.0, vcc
	v_mul_f32_e32 v107, v107, v84
	v_and_b32_e32 v84, 0xffff0000, v154
	v_cndmask_b32_e32 v87, v153, v87, vcc
	v_mul_f32_e32 v106, v106, v85
	v_rcp_f32_e32 v85, v84
	v_lshlrev_b32_e32 v86, 16, v154
	v_mul_f32_e32 v46, v46, v87
	v_rcp_f32_e32 v87, v86
	v_and_b32_e32 v152, 0xffff0000, v158
	v_mul_f32_e32 v85, v85, v152
	v_lshlrev_b32_e32 v153, 16, v158
	v_mul_f32_e32 v87, v87, v153
	v_cndmask_b32_e32 v85, v152, v85, vcc
	v_cndmask_b32_e64 v84, v84, 1.0, vcc
	v_cndmask_b32_e32 v87, v153, v87, vcc
	v_mul_f32_e32 v41, v41, v85
	v_cndmask_b32_e64 v85, v86, 1.0, vcc
	v_mul_f32_e32 v153, v97, v84
	v_and_b32_e32 v84, 0xffff0000, v155
	v_lshlrev_b32_e32 v86, 16, v155
	v_mul_f32_e32 v40, v40, v87
	v_mul_f32_e32 v152, v96, v85
	v_rcp_f32_e32 v85, v84
	v_rcp_f32_e32 v87, v86
	v_and_b32_e32 v96, 0xffff0000, v159
	v_lshlrev_b32_e32 v97, 16, v159
	v_mul_f32_e32 v85, v85, v96
	v_mul_f32_e32 v87, v87, v97
	v_cndmask_b32_e32 v87, v97, v87, vcc
	v_cndmask_b32_e32 v85, v96, v85, vcc
	v_mul_f32_e32 v42, v42, v87
	v_mul_f32_e32 v43, v43, v85
	v_cndmask_b32_e64 v85, v86, 1.0, vcc
	v_cndmask_b32_e64 v84, v84, 1.0, vcc
	v_mul_f32_e32 v154, v98, v85
	v_mul_f32_e32 v155, v99, v84
	s_waitcnt vmcnt(4)
	v_and_b32_e32 v84, 0xffff0000, v148
	v_rcp_f32_e32 v85, v84
	v_and_b32_e32 v96, 0xffff0000, v144
	v_lshlrev_b32_e32 v86, 16, v148
	v_lshlrev_b32_e32 v97, 16, v144
	v_mul_f32_e32 v85, v85, v96
	v_cndmask_b32_e32 v85, v96, v85, vcc
	v_mul_f32_e32 v13, v13, v85
	v_cndmask_b32_e64 v85, v86, 1.0, vcc
	v_mul_f32_e32 v144, v76, v85
	v_cndmask_b32_e64 v76, v84, 1.0, vcc
	v_mul_f32_e32 v148, v77, v76
	v_and_b32_e32 v76, 0xffff0000, v149
	v_rcp_f32_e32 v77, v76
	v_rcp_f32_e32 v87, v86
	v_and_b32_e32 v86, 0xffff0000, v145
	v_lshlrev_b32_e32 v84, 16, v149
	v_mul_f32_e32 v77, v77, v86
	v_mul_f32_e32 v87, v87, v97
	v_cndmask_b32_e32 v77, v86, v77, vcc
	v_cndmask_b32_e64 v76, v76, 1.0, vcc
	v_cndmask_b32_e32 v87, v97, v87, vcc
	v_mul_f32_e32 v15, v15, v77
	v_cndmask_b32_e64 v77, v84, 1.0, vcc
	v_mul_f32_e32 v149, v79, v76
	v_and_b32_e32 v76, 0xffff0000, v150
	v_mul_f32_e32 v12, v12, v87
	v_lshlrev_b32_e32 v87, 16, v145
	v_mul_f32_e32 v145, v78, v77
	v_rcp_f32_e32 v77, v76
	v_rcp_f32_e32 v85, v84
	v_and_b32_e32 v84, 0xffff0000, v146
	v_lshlrev_b32_e32 v78, 16, v150
	v_mul_f32_e32 v77, v77, v84
	v_mul_f32_e32 v85, v85, v87
	v_cndmask_b32_e32 v77, v84, v77, vcc
	v_cndmask_b32_e32 v85, v87, v85, vcc
	v_rcp_f32_e32 v79, v78
	v_mul_f32_e32 v9, v9, v77
	v_cndmask_b32_e64 v77, v78, 1.0, vcc
	v_mul_f32_e32 v14, v14, v85
	v_lshlrev_b32_e32 v85, 16, v146
	v_mul_f32_e32 v146, v72, v77
	v_cndmask_b32_e64 v72, v76, 1.0, vcc
	v_mul_f32_e32 v150, v73, v72
	v_and_b32_e32 v72, 0xffff0000, v151
	v_lshlrev_b32_e32 v76, 16, v151
	v_rcp_f32_e32 v73, v72
	v_rcp_f32_e32 v77, v76
	v_mul_f32_e32 v79, v79, v85
	v_cndmask_b32_e32 v79, v85, v79, vcc
	v_mul_f32_e32 v8, v8, v79
	v_and_b32_e32 v78, 0xffff0000, v147
	v_lshlrev_b32_e32 v79, 16, v147
	v_mul_f32_e32 v73, v73, v78
	v_mul_f32_e32 v77, v77, v79
	v_cndmask_b32_e32 v77, v79, v77, vcc
	v_cndmask_b32_e32 v73, v78, v73, vcc
	v_mul_f32_e32 v10, v10, v77
	v_mul_f32_e32 v11, v11, v73
	v_cndmask_b32_e64 v73, v76, 1.0, vcc
	v_cndmask_b32_e64 v72, v72, 1.0, vcc
	v_mul_f32_e32 v147, v74, v73
	v_mul_f32_e32 v151, v75, v72
	s_waitcnt vmcnt(2)
	v_and_b32_e32 v72, 0xffff0000, v136
	v_rcp_f32_e32 v73, v72
	v_lshlrev_b32_e32 v74, 16, v136
	v_rcp_f32_e32 v75, v74
	v_and_b32_e32 v76, 0xffff0000, v140
	v_mul_f32_e32 v73, v73, v76
	v_cndmask_b32_e32 v73, v76, v73, vcc
	v_cndmask_b32_e64 v72, v72, 1.0, vcc
	v_lshlrev_b32_e32 v77, 16, v140
	v_mul_f32_e32 v37, v37, v73
	v_cndmask_b32_e64 v73, v74, 1.0, vcc
	v_mul_f32_e32 v140, v89, v72
	v_and_b32_e32 v72, 0xffff0000, v137
	v_mul_f32_e32 v75, v75, v77
	v_mul_f32_e32 v136, v88, v73
	v_rcp_f32_e32 v73, v72
	v_cndmask_b32_e32 v75, v77, v75, vcc
	v_lshlrev_b32_e32 v74, 16, v137
	v_mul_f32_e32 v36, v36, v75
	v_rcp_f32_e32 v75, v74
	v_and_b32_e32 v76, 0xffff0000, v141
	v_mul_f32_e32 v73, v73, v76
	v_lshlrev_b32_e32 v77, 16, v141
	v_cndmask_b32_e32 v73, v76, v73, vcc
	v_cndmask_b32_e64 v72, v72, 1.0, vcc
	v_mul_f32_e32 v75, v75, v77
	v_mul_f32_e32 v39, v39, v73
	v_cndmask_b32_e64 v73, v74, 1.0, vcc
	v_mul_f32_e32 v141, v91, v72
	v_and_b32_e32 v72, 0xffff0000, v138
	v_cndmask_b32_e32 v75, v77, v75, vcc
	v_mul_f32_e32 v137, v90, v73
	v_rcp_f32_e32 v73, v72
	v_lshlrev_b32_e32 v74, 16, v138
	v_mul_f32_e32 v38, v38, v75
	v_rcp_f32_e32 v75, v74
	v_and_b32_e32 v76, 0xffff0000, v142
	v_mul_f32_e32 v73, v73, v76
	v_lshlrev_b32_e32 v77, 16, v142
	v_mul_f32_e32 v75, v75, v77
	v_cndmask_b32_e32 v73, v76, v73, vcc
	v_cndmask_b32_e64 v72, v72, 1.0, vcc
	v_cndmask_b32_e32 v75, v77, v75, vcc
	v_mul_f32_e32 v33, v33, v73
	v_cndmask_b32_e64 v73, v74, 1.0, vcc
	v_mul_f32_e32 v142, v81, v72
	v_and_b32_e32 v72, 0xffff0000, v139
	v_lshlrev_b32_e32 v74, 16, v139
	v_mul_f32_e32 v32, v32, v75
	v_mul_f32_e32 v138, v80, v73
	v_rcp_f32_e32 v73, v72
	v_rcp_f32_e32 v75, v74
	v_and_b32_e32 v76, 0xffff0000, v143
	v_lshlrev_b32_e32 v77, 16, v143
	v_mul_f32_e32 v73, v73, v76
	v_mul_f32_e32 v75, v75, v77
	v_cndmask_b32_e32 v75, v77, v75, vcc
	v_cndmask_b32_e32 v73, v76, v73, vcc
	v_mul_f32_e32 v34, v34, v75
	v_mul_f32_e32 v35, v35, v73
	v_cndmask_b32_e64 v73, v74, 1.0, vcc
	v_cndmask_b32_e64 v72, v72, 1.0, vcc
	v_mul_f32_e32 v139, v82, v73
	v_mul_f32_e32 v143, v83, v72
	s_waitcnt vmcnt(0)
; __device__ __forceinline__ void scale_acc_by_gate_ratio(f32x4 (&acc)[2][2][4][2], const bf16_t* ga_base, bool single, const Unit& u, int wr, int wc, int fr, int fq) {
;     ...
;     for (int bt = 0; bt < 2; ++bt) {
;         u32x4 X[8], Y[8];
; #pragma unroll
;         for (int m = 0; m < 4; ++m)
; #pragma unroll
;             for (int bj = 0; bj < 2; ++bj) {
;                 const bf16_t* p0 = gp + (size_t)(m * 16) * 3072 + bj * HALF; const bf16_t* p1 = p0 + (size_t)HALF * 3072;
;                 const bf16_t* px = bt == 0 ? p0 : GSEL(single, p0, p1);
;                 const bf16_t* py = bt == 0 ? GSEL(single, p1, p0 + 1024) : GSEL(single, p0, p1 + 1024);
;                 X[m * 2 + bj] = *(const u32x4*)px; Y[m * 2 + bj] = *(const u32x4*)py;
;             }
;         __builtin_amdgcn_sched_barrier(0);
; #pragma unroll
;         for (int m = 0; m < 4; ++m)
; #pragma unroll
;             for (int bj = 0; bj < 2; ++bj) {
;                 const u32x4 gx = X[m * 2 + bj], gy = Y[m * 2 + bj];
;                 const unsigned xw[4] = {gx.x, gx.y, gx.z, gx.w}, yw[4] = {gy.x, gy.y, gy.z, gy.w};
; #pragma unroll
;                 for (int w = 0; w < 4; ++w) {
;                     const float x_ = bf_lo(xw[w]), x2_ = bf_hi(xw[w]), y_ = bf_lo(yw[w]), y2_ = bf_hi(yw[w]);
;                     const float q_ = x_ * __builtin_amdgcn_rcpf(y_), q2_ = x2_ * __builtin_amdgcn_rcpf(y2_);
;                     const int n = w >> 1, e = (w & 1) * 2;
;                     if (bt == 0) {
;                         acc[0][bj][m][n][e] *= GSEL(single, x_, q_); acc[0][bj][m][n][e + 1] *= GSEL(single, x2_, q2_);
;                         acc[1][bj][m][n][e] *= GSEL(single, y_, 1.0f); acc[1][bj][m][n][e + 1] *= GSEL(single, y2_, 1.0f);
;                     } else {
;                         acc[1][bj][m][n][e] *= GSEL(single, 1.0f, q_); acc[1][bj][m][n][e + 1] *= GSEL(single, 1.0f, q2_);
;                     }
	v_and_b32_e32 v72, 0xffff0000, v132
	v_rcp_f32_e32 v73, v72
	v_and_b32_e32 v76, 0xffff0000, v128
	v_lshlrev_b32_e32 v74, 16, v132
	v_rcp_f32_e32 v75, v74
	v_mul_f32_e32 v73, v73, v76
	v_cndmask_b32_e32 v73, v76, v73, vcc
	v_mul_f32_e32 v5, v5, v73
	v_cndmask_b32_e64 v73, v74, 1.0, vcc
	v_mul_f32_e32 v132, v68, v73
	v_cndmask_b32_e64 v68, v72, 1.0, vcc
	v_mul_f32_e32 v156, v69, v68
	v_and_b32_e32 v68, 0xffff0000, v133
	v_rcp_f32_e32 v69, v68
	v_and_b32_e32 v74, 0xffff0000, v129
	v_lshlrev_b32_e32 v72, 16, v133
	v_cndmask_b32_e64 v68, v68, 1.0, vcc
	v_mul_f32_e32 v69, v69, v74
	v_cndmask_b32_e32 v69, v74, v69, vcc
	v_mul_f32_e32 v7, v7, v69
	v_cndmask_b32_e64 v69, v72, 1.0, vcc
	v_mul_f32_e32 v157, v71, v68
	v_and_b32_e32 v68, 0xffff0000, v134
	v_mul_f32_e32 v133, v70, v69
	v_rcp_f32_e32 v69, v68
	v_lshlrev_b32_e32 v77, 16, v128
	v_rcp_f32_e32 v73, v72
	v_and_b32_e32 v72, 0xffff0000, v130
	v_mul_f32_e32 v75, v75, v77
	v_mul_f32_e32 v69, v69, v72
	v_cndmask_b32_e32 v75, v77, v75, vcc
	v_lshlrev_b32_e32 v70, 16, v134
	v_cndmask_b32_e32 v69, v72, v69, vcc
	v_mul_f32_e32 v4, v4, v75
	v_lshlrev_b32_e32 v75, 16, v129
	v_rcp_f32_e32 v71, v70
	v_mul_f32_e32 v1, v1, v69
	v_cndmask_b32_e64 v69, v70, 1.0, vcc
	v_mul_f32_e32 v73, v73, v75
	v_mul_f32_e32 v134, v64, v69
	v_cndmask_b32_e64 v64, v68, 1.0, vcc
	v_cndmask_b32_e32 v73, v75, v73, vcc
	v_mul_f32_e32 v158, v65, v64
	v_and_b32_e32 v64, 0xffff0000, v135
	v_lshlrev_b32_e32 v68, 16, v135
	v_mul_f32_e32 v6, v6, v73
	v_lshlrev_b32_e32 v73, 16, v130
	v_rcp_f32_e32 v65, v64
	v_rcp_f32_e32 v69, v68
	v_mul_f32_e32 v71, v71, v73
	v_cndmask_b32_e32 v71, v73, v71, vcc
	v_mul_f32_e32 v0, v0, v71
	v_and_b32_e32 v70, 0xffff0000, v131
	v_lshlrev_b32_e32 v71, 16, v131
	v_mul_f32_e32 v65, v65, v70
	v_mul_f32_e32 v69, v69, v71
	v_cndmask_b32_e32 v69, v71, v69, vcc
	v_cndmask_b32_e32 v65, v70, v65, vcc
	v_mul_f32_e32 v2, v2, v69
	v_mul_f32_e32 v3, v3, v65
	v_cndmask_b32_e64 v65, v68, 1.0, vcc
	v_cndmask_b32_e64 v64, v64, 1.0, vcc
	v_mul_f32_e32 v135, v66, v65
	v_mul_f32_e32 v159, v67, v64
	v_cndmask_b32_e32 v65, v195, v197, vcc
	v_cndmask_b32_e32 v64, v194, v196, vcc
	global_load_dwordx4 v[164:167], v[64:65], off
	v_cndmask_b32_e32 v65, v225, v199, vcc
	v_cndmask_b32_e32 v64, v224, v198, vcc
	v_lshl_add_u64 v[66:67], v[194:195], 0, s[94:95]
	global_load_dwordx4 v[168:171], v[64:65], off
	global_load_dwordx4 v[172:175], v[66:67], off
	global_load_dwordx4 v[180:183], v[66:67], off offset:256
	v_cndmask_b32_e32 v65, v223, v201, vcc
	v_cndmask_b32_e32 v64, v222, v200, vcc
	global_load_dwordx4 v[194:197], v[64:65], off
	v_cndmask_b32_e32 v65, v221, v203, vcc
	v_cndmask_b32_e32 v64, v220, v202, vcc
	v_lshl_add_u64 v[66:67], v[222:223], 0, s[94:95]
	v_lshl_add_u64 v[68:69], v[220:221], 0, s[94:95]
	global_load_dwordx4 v[84:87], v[64:65], off
	global_load_dwordx4 v[198:201], v[66:67], off
	global_load_dwordx4 v[220:223], v[68:69], off
	v_cndmask_b32_e32 v65, v219, v205, vcc
	v_cndmask_b32_e32 v64, v218, v204, vcc
	global_load_dwordx4 v[76:79], v[64:65], off
	v_cndmask_b32_e32 v65, v217, v207, vcc
	v_cndmask_b32_e32 v64, v216, v206, vcc
	v_lshl_add_u64 v[66:67], v[218:219], 0, s[94:95]
	v_lshl_add_u64 v[68:69], v[216:217], 0, s[94:95]
	global_load_dwordx4 v[72:75], v[64:65], off
	global_load_dwordx4 v[96:99], v[66:67], off
	global_load_dwordx4 v[88:91], v[68:69], off
	v_cndmask_b32_e32 v65, v215, v209, vcc
	v_cndmask_b32_e32 v64, v214, v208, vcc
	v_lshl_add_u64 v[80:81], v[214:215], 0, s[94:95]
	global_load_dwordx4 v[68:71], v[64:65], off
	v_cndmask_b32_e32 v65, v213, v211, vcc
	v_cndmask_b32_e32 v64, v212, v210, vcc
	v_lshl_add_u64 v[128:129], v[212:213], 0, s[94:95]
	global_load_dwordx4 v[64:67], v[64:65], off
	s_nop 0
	global_load_dwordx4 v[80:83], v[80:81], off
	s_nop 0
	global_load_dwordx4 v[128:131], v[128:129], off
	s_waitcnt vmcnt(13)
	v_and_b32_e32 v178, 0xffff0000, v172
	v_lshlrev_b32_e32 v172, 16, v172
	v_rcp_f32_e32 v172, v172
	v_rcp_f32_e32 v178, v178
	v_and_b32_e32 v193, 0xffff0000, v164
	v_lshlrev_b32_e32 v164, 16, v164
	v_mul_f32_e32 v164, v172, v164
	v_mul_f32_e32 v178, v178, v193
	v_cndmask_b32_e32 v164, 1.0, v164, vcc
	v_mul_f32_e32 v124, v124, v164
	v_cndmask_b32_e32 v164, 1.0, v178, vcc
	v_mul_f32_e32 v125, v125, v164
	v_and_b32_e32 v164, 0xffff0000, v173
	v_rcp_f32_e32 v164, v164
	v_lshlrev_b32_e32 v172, 16, v173
	v_rcp_f32_e32 v172, v172
	v_and_b32_e32 v173, 0xffff0000, v165
	v_mul_f32_e32 v164, v164, v173
	v_lshlrev_b32_e32 v165, 16, v165
	v_mul_f32_e32 v165, v172, v165
	v_cndmask_b32_e32 v164, 1.0, v164, vcc
	v_cndmask_b32_e32 v165, 1.0, v165, vcc
	v_mul_f32_e32 v127, v127, v164
	v_and_b32_e32 v164, 0xffff0000, v174
	v_mul_f32_e32 v126, v126, v165
	v_rcp_f32_e32 v164, v164
	v_lshlrev_b32_e32 v165, 16, v174
	v_rcp_f32_e32 v165, v165
	v_and_b32_e32 v172, 0xffff0000, v166
	v_mul_f32_e32 v164, v164, v172
	v_lshlrev_b32_e32 v166, 16, v166
	v_mul_f32_e32 v165, v165, v166
	v_cndmask_b32_e32 v164, 1.0, v164, vcc
	v_cndmask_b32_e32 v165, 1.0, v165, vcc
	v_mul_f32_e32 v121, v121, v164
	v_and_b32_e32 v164, 0xffff0000, v175
	v_mul_f32_e32 v120, v120, v165
	v_rcp_f32_e32 v164, v164
	v_lshlrev_b32_e32 v165, 16, v175
	v_rcp_f32_e32 v165, v165
	v_and_b32_e32 v166, 0xffff0000, v167
	v_mul_f32_e32 v164, v164, v166
	v_lshlrev_b32_e32 v166, 16, v167
	v_mul_f32_e32 v165, v165, v166
	v_cndmask_b32_e32 v165, 1.0, v165, vcc
	v_cndmask_b32_e32 v164, 1.0, v164, vcc
	v_mul_f32_e32 v122, v122, v165
	v_mul_f32_e32 v123, v123, v164
	s_waitcnt vmcnt(12)
; __device__ __forceinline__ void scale_acc_by_gate_ratio(f32x4 (&acc)[2][2][4][2], const bf16_t* ga_base, bool single, const Unit& u, int wr, int wc, int fr, int fq) {
;     ...
;         for (int m = 0; m < 4; ++m)
; #pragma unroll
;             for (int bj = 0; bj < 2; ++bj) {
;                 const u32x4 gx = X[m * 2 + bj], gy = Y[m * 2 + bj];
;                 const unsigned xw[4] = {gx.x, gx.y, gx.z, gx.w}, yw[4] = {gy.x, gy.y, gy.z, gy.w};
; #pragma unroll
;                 for (int w = 0; w < 4; ++w) {
;                     const float x_ = bf_lo(xw[w]), x2_ = bf_hi(xw[w]), y_ = bf_lo(yw[w]), y2_ = bf_hi(yw[w]);
;                     const float q_ = x_ * __builtin_amdgcn_rcpf(y_), q2_ = x2_ * __builtin_amdgcn_rcpf(y2_);
;                     const int n = w >> 1, e = (w & 1) * 2;
;                     if (bt == 0) {
;                         acc[0][bj][m][n][e] *= GSEL(single, x_, q_); acc[0][bj][m][n][e + 1] *= GSEL(single, x2_, q2_);
;                         acc[1][bj][m][n][e] *= GSEL(single, y_, 1.0f); acc[1][bj][m][n][e + 1] *= GSEL(single, y2_, 1.0f);
;                     } else {
;                         acc[1][bj][m][n][e] *= GSEL(single, 1.0f, q_); acc[1][bj][m][n][e + 1] *= GSEL(single, 1.0f, q2_);
;                     }
;                 }
	v_and_b32_e32 v164, 0xffff0000, v180
	v_rcp_f32_e32 v164, v164
	v_lshlrev_b32_e32 v165, 16, v180
	v_rcp_f32_e32 v165, v165
	v_and_b32_e32 v166, 0xffff0000, v168
	v_mul_f32_e32 v164, v164, v166
	v_lshlrev_b32_e32 v166, 16, v168
	v_mul_f32_e32 v165, v165, v166
	v_cndmask_b32_e32 v164, 1.0, v164, vcc
	v_cndmask_b32_e32 v165, 1.0, v165, vcc
	v_mul_f32_e32 v109, v109, v164
	v_and_b32_e32 v164, 0xffff0000, v181
	v_mul_f32_e32 v108, v108, v165
	v_rcp_f32_e32 v164, v164
	v_lshlrev_b32_e32 v165, 16, v181
	v_rcp_f32_e32 v165, v165
	v_and_b32_e32 v166, 0xffff0000, v169
	v_mul_f32_e32 v164, v164, v166
	v_lshlrev_b32_e32 v166, 16, v169
	v_mul_f32_e32 v165, v165, v166
	v_cndmask_b32_e32 v164, 1.0, v164, vcc
	v_cndmask_b32_e32 v165, 1.0, v165, vcc
	v_mul_f32_e32 v111, v111, v164
	v_and_b32_e32 v164, 0xffff0000, v182
	v_mul_f32_e32 v110, v110, v165
	v_rcp_f32_e32 v164, v164
	v_lshlrev_b32_e32 v165, 16, v182
	v_rcp_f32_e32 v165, v165
	v_and_b32_e32 v166, 0xffff0000, v170
	v_mul_f32_e32 v164, v164, v166
	v_lshlrev_b32_e32 v166, 16, v170
	v_mul_f32_e32 v165, v165, v166
	v_cndmask_b32_e32 v164, 1.0, v164, vcc
	v_cndmask_b32_e32 v165, 1.0, v165, vcc
	v_mul_f32_e32 v101, v101, v164
	v_and_b32_e32 v164, 0xffff0000, v183
	v_mul_f32_e32 v100, v100, v165
	v_rcp_f32_e32 v164, v164
	v_lshlrev_b32_e32 v165, 16, v183
	v_rcp_f32_e32 v165, v165
	v_and_b32_e32 v166, 0xffff0000, v171
	v_mul_f32_e32 v164, v164, v166
	v_lshlrev_b32_e32 v166, 16, v171
	v_mul_f32_e32 v165, v165, v166
	v_cndmask_b32_e32 v165, 1.0, v165, vcc
	v_cndmask_b32_e32 v164, 1.0, v164, vcc
	v_mul_f32_e32 v102, v102, v165
	v_mul_f32_e32 v103, v103, v164
	s_waitcnt vmcnt(9)
	v_and_b32_e32 v164, 0xffff0000, v198
	v_rcp_f32_e32 v164, v164
	v_lshlrev_b32_e32 v165, 16, v198
	v_rcp_f32_e32 v165, v165
	v_and_b32_e32 v166, 0xffff0000, v194
	v_mul_f32_e32 v164, v164, v166
	v_lshlrev_b32_e32 v166, 16, v194
	v_mul_f32_e32 v165, v165, v166
	v_cndmask_b32_e32 v164, 1.0, v164, vcc
	v_cndmask_b32_e32 v165, 1.0, v165, vcc
	v_mul_f32_e32 v117, v117, v164
	v_and_b32_e32 v164, 0xffff0000, v199
	v_mul_f32_e32 v116, v116, v165
	v_rcp_f32_e32 v164, v164
	v_lshlrev_b32_e32 v165, 16, v199
	v_rcp_f32_e32 v165, v165
	v_and_b32_e32 v166, 0xffff0000, v195
	v_mul_f32_e32 v164, v164, v166
	v_lshlrev_b32_e32 v166, 16, v195
	v_mul_f32_e32 v165, v165, v166
	v_cndmask_b32_e32 v164, 1.0, v164, vcc
	v_cndmask_b32_e32 v165, 1.0, v165, vcc
	v_mul_f32_e32 v119, v119, v164
	v_and_b32_e32 v164, 0xffff0000, v200
	v_mul_f32_e32 v118, v118, v165
	v_rcp_f32_e32 v164, v164
	v_lshlrev_b32_e32 v165, 16, v200
	v_rcp_f32_e32 v165, v165
	v_and_b32_e32 v166, 0xffff0000, v196
	v_mul_f32_e32 v164, v164, v166
	v_lshlrev_b32_e32 v166, 16, v196
	v_mul_f32_e32 v165, v165, v166
	v_cndmask_b32_e32 v164, 1.0, v164, vcc
	v_cndmask_b32_e32 v165, 1.0, v165, vcc
	v_mul_f32_e32 v113, v113, v164
	v_and_b32_e32 v164, 0xffff0000, v201
	v_mul_f32_e32 v112, v112, v165
	v_rcp_f32_e32 v164, v164
	v_lshlrev_b32_e32 v165, 16, v201
	v_rcp_f32_e32 v165, v165
	v_and_b32_e32 v166, 0xffff0000, v197
	v_mul_f32_e32 v164, v164, v166
	v_lshlrev_b32_e32 v166, 16, v197
	v_mul_f32_e32 v165, v165, v166
	v_cndmask_b32_e32 v165, 1.0, v165, vcc
	v_cndmask_b32_e32 v164, 1.0, v164, vcc
	v_mul_f32_e32 v114, v114, v165
	v_mul_f32_e32 v115, v115, v164
	s_waitcnt vmcnt(8)
	v_lshlrev_b32_e32 v165, 16, v220
	v_and_b32_e32 v164, 0xffff0000, v220
	v_rcp_f32_e32 v165, v165
	v_rcp_f32_e32 v164, v164
	v_and_b32_e32 v166, 0xffff0000, v84
	v_lshlrev_b32_e32 v84, 16, v84
	v_mul_f32_e32 v84, v165, v84
	v_mul_f32_e32 v164, v164, v166
	v_cndmask_b32_e32 v84, 1.0, v84, vcc
	v_mul_f32_e32 v92, v92, v84
	v_cndmask_b32_e32 v84, 1.0, v164, vcc
	v_mul_f32_e32 v93, v93, v84
	v_and_b32_e32 v84, 0xffff0000, v221
	v_rcp_f32_e32 v84, v84
	v_lshlrev_b32_e32 v164, 16, v221
	v_rcp_f32_e32 v164, v164
	v_and_b32_e32 v165, 0xffff0000, v85
	v_mul_f32_e32 v84, v84, v165
	v_lshlrev_b32_e32 v85, 16, v85
	v_mul_f32_e32 v85, v164, v85
	v_cndmask_b32_e32 v84, 1.0, v84, vcc
	v_cndmask_b32_e32 v85, 1.0, v85, vcc
	v_mul_f32_e32 v95, v95, v84
	v_and_b32_e32 v84, 0xffff0000, v222
	v_mul_f32_e32 v94, v94, v85
	v_rcp_f32_e32 v84, v84
	v_lshlrev_b32_e32 v85, 16, v222
	v_rcp_f32_e32 v85, v85
	v_and_b32_e32 v164, 0xffff0000, v86
	v_mul_f32_e32 v164, v84, v164
	v_lshlrev_b32_e32 v84, 16, v86
	v_mul_f32_e32 v84, v85, v84
	v_cndmask_b32_e32 v84, 1.0, v84, vcc
	v_and_b32_e32 v86, 0xffff0000, v223
	v_mul_f32_e32 v84, v160, v84
	v_rcp_f32_e32 v86, v86
	v_lshlrev_b32_e32 v160, 16, v223
	v_rcp_f32_e32 v160, v160
	v_cndmask_b32_e32 v85, 1.0, v164, vcc
	v_mul_f32_e32 v85, v161, v85
	v_and_b32_e32 v161, 0xffff0000, v87
	v_mul_f32_e32 v161, v86, v161
	v_lshlrev_b32_e32 v86, 16, v87
	v_mul_f32_e32 v86, v160, v86
	v_cndmask_b32_e32 v86, 1.0, v86, vcc
	v_cndmask_b32_e32 v87, 1.0, v161, vcc
	v_mul_f32_e32 v86, v162, v86
	v_mul_f32_e32 v87, v163, v87
	s_waitcnt vmcnt(5)
	v_and_b32_e32 v160, 0xffff0000, v96
	v_lshlrev_b32_e32 v96, 16, v96
	v_rcp_f32_e32 v96, v96
	v_rcp_f32_e32 v160, v160
	v_and_b32_e32 v161, 0xffff0000, v76
	v_lshlrev_b32_e32 v76, 16, v76
	v_mul_f32_e32 v76, v96, v76
	v_mul_f32_e32 v160, v160, v161
	v_cndmask_b32_e32 v76, 1.0, v76, vcc
	v_mul_f32_e32 v104, v104, v76
	v_cndmask_b32_e32 v76, 1.0, v160, vcc
	v_mul_f32_e32 v105, v105, v76
	v_and_b32_e32 v76, 0xffff0000, v97
	v_rcp_f32_e32 v76, v76
	v_lshlrev_b32_e32 v96, 16, v97
	v_rcp_f32_e32 v96, v96
	v_and_b32_e32 v97, 0xffff0000, v77
	v_mul_f32_e32 v76, v76, v97
	v_lshlrev_b32_e32 v77, 16, v77
	v_mul_f32_e32 v77, v96, v77
	v_cndmask_b32_e32 v76, 1.0, v76, vcc
	v_cndmask_b32_e32 v77, 1.0, v77, vcc
	v_mul_f32_e32 v107, v107, v76
	v_and_b32_e32 v76, 0xffff0000, v98
	v_mul_f32_e32 v106, v106, v77
	v_rcp_f32_e32 v76, v76
	v_lshlrev_b32_e32 v77, 16, v98
	v_rcp_f32_e32 v77, v77
	v_and_b32_e32 v96, 0xffff0000, v78
	v_mul_f32_e32 v76, v76, v96
	v_lshlrev_b32_e32 v78, 16, v78
	v_mul_f32_e32 v77, v77, v78
	v_cndmask_b32_e32 v76, 1.0, v76, vcc
	v_cndmask_b32_e32 v77, 1.0, v77, vcc
	v_mul_f32_e32 v97, v153, v76
	v_and_b32_e32 v76, 0xffff0000, v99
	v_mul_f32_e32 v96, v152, v77
	v_rcp_f32_e32 v76, v76
	v_lshlrev_b32_e32 v77, 16, v99
	v_rcp_f32_e32 v77, v77
	v_and_b32_e32 v78, 0xffff0000, v79
	v_mul_f32_e32 v76, v76, v78
	v_lshlrev_b32_e32 v78, 16, v79
	v_mul_f32_e32 v77, v77, v78
	v_cndmask_b32_e32 v77, 1.0, v77, vcc
	v_cndmask_b32_e32 v76, 1.0, v76, vcc
	v_mul_f32_e32 v98, v154, v77
	v_mul_f32_e32 v99, v155, v76
	s_waitcnt vmcnt(4)
; __device__ __forceinline__ void scale_acc_by_gate_ratio(f32x4 (&acc)[2][2][4][2], const bf16_t* ga_base, bool single, const Unit& u, int wr, int wc, int fr, int fq) {
;     ...
;         for (int m = 0; m < 4; ++m)
; #pragma unroll
;             for (int bj = 0; bj < 2; ++bj) {
;                 const u32x4 gx = X[m * 2 + bj], gy = Y[m * 2 + bj];
;                 const unsigned xw[4] = {gx.x, gx.y, gx.z, gx.w}, yw[4] = {gy.x, gy.y, gy.z, gy.w};
; #pragma unroll
;                 for (int w = 0; w < 4; ++w) {
;                     const float x_ = bf_lo(xw[w]), x2_ = bf_hi(xw[w]), y_ = bf_lo(yw[w]), y2_ = bf_hi(yw[w]);
;                     const float q_ = x_ * __builtin_amdgcn_rcpf(y_), q2_ = x2_ * __builtin_amdgcn_rcpf(y2_);
;                     const int n = w >> 1, e = (w & 1) * 2;
;                     if (bt == 0) {
;                         acc[0][bj][m][n][e] *= GSEL(single, x_, q_); acc[0][bj][m][n][e + 1] *= GSEL(single, x2_, q2_);
;                         acc[1][bj][m][n][e] *= GSEL(single, y_, 1.0f); acc[1][bj][m][n][e + 1] *= GSEL(single, y2_, 1.0f);
;                     } else {
;                         acc[1][bj][m][n][e] *= GSEL(single, 1.0f, q_); acc[1][bj][m][n][e + 1] *= GSEL(single, 1.0f, q2_);
;                     }
;                 }
;     __device__ __forceinline__ void operator()(f32x4 (&acc)[2][2][4][2], const SubUnit& su, int wr, int wc, int fr, int fq) const {
;     ...
;         if (br == 2) Epi<0>{Qp, DM, nullptr, nullptr, nullptr, nullptr}(acc, u, wr, wc, fr, fq);
	v_lshlrev_b32_e32 v77, 16, v88
	v_and_b32_e32 v76, 0xffff0000, v88
	v_rcp_f32_e32 v77, v77
	v_rcp_f32_e32 v76, v76
	v_and_b32_e32 v78, 0xffff0000, v72
	v_lshlrev_b32_e32 v72, 16, v72
	v_mul_f32_e32 v72, v77, v72
	v_mul_f32_e32 v78, v76, v78
	v_cndmask_b32_e32 v72, 1.0, v72, vcc
	v_mul_f32_e32 v76, v144, v72
	v_cndmask_b32_e32 v72, 1.0, v78, vcc
	v_mul_f32_e32 v77, v148, v72
	v_and_b32_e32 v72, 0xffff0000, v89
	v_rcp_f32_e32 v72, v72
	v_lshlrev_b32_e32 v78, 16, v89
	v_rcp_f32_e32 v78, v78
	v_and_b32_e32 v79, 0xffff0000, v73
	v_mul_f32_e32 v72, v72, v79
	v_lshlrev_b32_e32 v73, 16, v73
	v_mul_f32_e32 v73, v78, v73
	v_cndmask_b32_e32 v72, 1.0, v72, vcc
	v_cndmask_b32_e32 v73, 1.0, v73, vcc
	v_mul_f32_e32 v79, v149, v72
	v_and_b32_e32 v72, 0xffff0000, v90
	v_mul_f32_e32 v78, v145, v73
	v_rcp_f32_e32 v72, v72
	v_lshlrev_b32_e32 v73, 16, v90
	v_rcp_f32_e32 v73, v73
	v_and_b32_e32 v88, 0xffff0000, v74
	v_mul_f32_e32 v88, v72, v88
	v_lshlrev_b32_e32 v72, 16, v74
	v_and_b32_e32 v74, 0xffff0000, v91
	v_mul_f32_e32 v72, v73, v72
	v_cndmask_b32_e32 v73, 1.0, v88, vcc
	v_rcp_f32_e32 v74, v74
	v_lshlrev_b32_e32 v88, 16, v91
	v_rcp_f32_e32 v88, v88
	v_and_b32_e32 v89, 0xffff0000, v75
	v_mul_f32_e32 v89, v74, v89
	v_lshlrev_b32_e32 v74, 16, v75
	v_mul_f32_e32 v74, v88, v74
	v_cndmask_b32_e32 v72, 1.0, v72, vcc
	v_cndmask_b32_e32 v74, 1.0, v74, vcc
	v_cndmask_b32_e32 v75, 1.0, v89, vcc
	v_mul_f32_e32 v72, v146, v72
	v_mul_f32_e32 v73, v150, v73
	v_mul_f32_e32 v74, v147, v74
	v_mul_f32_e32 v75, v151, v75
	s_waitcnt vmcnt(1)
	v_and_b32_e32 v88, 0xffff0000, v80
	v_lshlrev_b32_e32 v80, 16, v80
	v_rcp_f32_e32 v80, v80
	v_rcp_f32_e32 v88, v88
	v_and_b32_e32 v89, 0xffff0000, v68
	v_lshlrev_b32_e32 v68, 16, v68
	v_mul_f32_e32 v68, v80, v68
	v_mul_f32_e32 v89, v88, v89
	v_cndmask_b32_e32 v68, 1.0, v68, vcc
	v_mul_f32_e32 v88, v136, v68
	v_cndmask_b32_e32 v68, 1.0, v89, vcc
	v_mul_f32_e32 v89, v140, v68
	v_and_b32_e32 v68, 0xffff0000, v81
	v_rcp_f32_e32 v68, v68
	v_lshlrev_b32_e32 v80, 16, v81
	v_rcp_f32_e32 v80, v80
	v_and_b32_e32 v81, 0xffff0000, v69
	v_mul_f32_e32 v68, v68, v81
	v_lshlrev_b32_e32 v69, 16, v69
	v_mul_f32_e32 v69, v80, v69
	v_cndmask_b32_e32 v68, 1.0, v68, vcc
	v_cndmask_b32_e32 v69, 1.0, v69, vcc
	v_mul_f32_e32 v91, v141, v68
	v_and_b32_e32 v68, 0xffff0000, v82
	v_mul_f32_e32 v90, v137, v69
	v_rcp_f32_e32 v68, v68
	v_lshlrev_b32_e32 v69, 16, v82
	v_rcp_f32_e32 v69, v69
	v_and_b32_e32 v80, 0xffff0000, v70
	v_mul_f32_e32 v68, v68, v80
	v_lshlrev_b32_e32 v70, 16, v70
	v_mul_f32_e32 v69, v69, v70
	v_cndmask_b32_e32 v68, 1.0, v68, vcc
	v_cndmask_b32_e32 v69, 1.0, v69, vcc
	v_mul_f32_e32 v81, v142, v68
	v_and_b32_e32 v68, 0xffff0000, v83
	v_mul_f32_e32 v80, v138, v69
	v_rcp_f32_e32 v68, v68
	v_lshlrev_b32_e32 v69, 16, v83
	v_rcp_f32_e32 v69, v69
	v_and_b32_e32 v70, 0xffff0000, v71
	v_mul_f32_e32 v68, v68, v70
	v_lshlrev_b32_e32 v70, 16, v71
	v_mul_f32_e32 v69, v69, v70
	v_cndmask_b32_e32 v69, 1.0, v69, vcc
	v_cndmask_b32_e32 v68, 1.0, v68, vcc
	v_mul_f32_e32 v82, v139, v69
	v_mul_f32_e32 v83, v143, v68
	s_waitcnt vmcnt(0)
	v_lshlrev_b32_e32 v69, 16, v128
	v_and_b32_e32 v68, 0xffff0000, v128
	v_rcp_f32_e32 v69, v69
	v_rcp_f32_e32 v68, v68
	v_and_b32_e32 v70, 0xffff0000, v64
	v_lshlrev_b32_e32 v64, 16, v64
	v_mul_f32_e32 v64, v69, v64
	v_mul_f32_e32 v70, v68, v70
	v_cndmask_b32_e32 v64, 1.0, v64, vcc
	v_mul_f32_e32 v68, v132, v64
	v_cndmask_b32_e32 v64, 1.0, v70, vcc
	v_mul_f32_e32 v69, v156, v64
	v_and_b32_e32 v64, 0xffff0000, v129
	v_rcp_f32_e32 v64, v64
	v_lshlrev_b32_e32 v70, 16, v129
	v_rcp_f32_e32 v70, v70
	v_and_b32_e32 v71, 0xffff0000, v65
	v_mul_f32_e32 v64, v64, v71
	v_lshlrev_b32_e32 v65, 16, v65
	v_mul_f32_e32 v65, v70, v65
	v_cndmask_b32_e32 v64, 1.0, v64, vcc
	v_cndmask_b32_e32 v65, 1.0, v65, vcc
	v_mul_f32_e32 v71, v157, v64
	v_and_b32_e32 v64, 0xffff0000, v130
	v_mul_f32_e32 v70, v133, v65
	v_rcp_f32_e32 v64, v64
	v_lshlrev_b32_e32 v65, 16, v130
	v_rcp_f32_e32 v65, v65
	v_and_b32_e32 v128, 0xffff0000, v66
	v_mul_f32_e32 v128, v64, v128
	v_lshlrev_b32_e32 v64, 16, v66
	v_and_b32_e32 v66, 0xffff0000, v131
	v_mul_f32_e32 v64, v65, v64
	v_cndmask_b32_e32 v65, 1.0, v128, vcc
	v_rcp_f32_e32 v66, v66
	v_lshlrev_b32_e32 v128, 16, v131
	v_rcp_f32_e32 v128, v128
	v_and_b32_e32 v129, 0xffff0000, v67
	v_mul_f32_e32 v129, v66, v129
	v_lshlrev_b32_e32 v66, 16, v67
	v_mul_f32_e32 v66, v128, v66
	v_cndmask_b32_e32 v64, 1.0, v64, vcc
	v_cndmask_b32_e32 v66, 1.0, v66, vcc
	v_cndmask_b32_e32 v67, 1.0, v129, vcc
	v_mul_f32_e32 v64, v134, v64
	v_mul_f32_e32 v65, v158, v65
	v_mul_f32_e32 v66, v135, v66
	v_mul_f32_e32 v67, v159, v67
	s_cmp_lg_u32 s13, 2
	s_cbranch_scc1 .LBB0_49
; __device__ __forceinline__ unsigned pk2(float lo, float hi) { f32v2 v = {lo, hi}; bf16v2 r = __builtin_convertvector(v, bf16v2); return __builtin_bit_cast(unsigned, r); }
;     __device__ __forceinline__ void operator()(f32x4 (&acc)[2][2][4][2], const Unit& u, int wr, int wc, int fr, int fq) const {
;     ...
; #pragma unroll
;         for (int ai = 0; ai < 2; ++ai)
; #pragma unroll
;             for (int m = 0; m < 4; ++m) {
;                 const size_t row = (size_t)(row0 + ai * HALF + m * 16);
; #pragma unroll
;                 for (int bj = 0; bj < 2; ++bj) {
;                     f32x4 v0 = acc[ai][bj][m][0], v1 = acc[ai][bj][m][1];
;                     const int cl = cl0 + bj * HALF;
;                     if constexpr (MODE == 0 || MODE == 1) {
;                         if (MODE == 1) {
; #pragma unroll
;                             for (int e = 0; e < 4; ++e) { const float a = fmaxf(v0[e], 0.f), b = fmaxf(v1[e], 0.f); v0[e] = a * a; v1[e] = b * b; }
;                         }
;                         u32x4 w; w.x = pk2(v0[0], v0[1]); w.y = pk2(v0[2], v0[3]); w.z = pk2(v1[0], v1[1]); w.w = pk2(v1[2], v1[3]);
;                         if constexpr (MODE == 1) __builtin_nontemporal_store(w, (u32x4*)(O + row * ldc + u.pn * BM + cl));
;                         else *(u32x4*)(O + row * ldc + u.pn * BM + cl) = w;
	v_ashrrev_i32_e32 v193, 31, v192
	v_lshlrev_b64 v[128:129], 11, v[192:193]
	s_ashr_i32 s27, s26, 31
	v_lshl_add_u64 v[132:133], s[92:93], 0, v[128:129]
	s_lshl_b64 s[6:7], s[26:27], 1
	v_lshl_add_u64 v[132:133], v[132:133], 0, s[6:7]
	v_lshlrev_b32_e32 v178, 1, v188
	v_cvt_pk_bf16_f32 v128, v60, v61
	v_cvt_pk_bf16_f32 v129, v62, v63
	v_cvt_pk_bf16_f32 v130, v56, v57
	v_cvt_pk_bf16_f32 v131, v58, v59
	v_lshl_add_u64 v[132:133], v[132:133], 0, v[178:179]
	global_store_dwordx4 v[132:133], v[128:131], off
	s_nop 1
	v_cvt_pk_bf16_f32 v128, v28, v29
	v_cvt_pk_bf16_f32 v129, v30, v31
	v_cvt_pk_bf16_f32 v130, v24, v25
	v_cvt_pk_bf16_f32 v131, v26, v27
	global_store_dwordx4 v[132:133], v[128:131], off offset:256
	s_nop 1
	v_or_b32_e32 v128, 16, v192
	v_ashrrev_i32_e32 v129, 31, v128
	v_lshlrev_b64 v[128:129], 11, v[128:129]
	v_lshl_add_u64 v[134:135], s[92:93], 0, v[128:129]
	v_lshl_add_u64 v[134:135], v[134:135], 0, s[6:7]
	v_cvt_pk_bf16_f32 v128, v52, v53
	v_cvt_pk_bf16_f32 v129, v54, v55
	v_cvt_pk_bf16_f32 v130, v48, v49
	v_cvt_pk_bf16_f32 v131, v50, v51
	v_lshl_add_u64 v[134:135], v[134:135], 0, v[178:179]
	global_store_dwordx4 v[134:135], v[128:131], off
	s_nop 1
	v_cvt_pk_bf16_f32 v128, v20, v21
	v_cvt_pk_bf16_f32 v129, v22, v23
	v_cvt_pk_bf16_f32 v130, v16, v17
	v_cvt_pk_bf16_f32 v131, v18, v19
	global_store_dwordx4 v[134:135], v[128:131], off offset:256
	s_nop 1
	v_or_b32_e32 v128, 32, v192
	v_ashrrev_i32_e32 v129, 31, v128
	v_lshlrev_b64 v[128:129], 11, v[128:129]
	v_lshl_add_u64 v[134:135], s[92:93], 0, v[128:129]
	v_lshl_add_u64 v[134:135], v[134:135], 0, s[6:7]
	v_cvt_pk_bf16_f32 v128, v44, v45
	v_cvt_pk_bf16_f32 v129, v46, v47
	v_cvt_pk_bf16_f32 v130, v40, v41
	v_cvt_pk_bf16_f32 v131, v42, v43
	v_lshl_add_u64 v[134:135], v[134:135], 0, v[178:179]
	global_store_dwordx4 v[134:135], v[128:131], off
	s_nop 1
	v_cvt_pk_bf16_f32 v128, v12, v13
	v_cvt_pk_bf16_f32 v129, v14, v15
	v_cvt_pk_bf16_f32 v130, v8, v9
	v_cvt_pk_bf16_f32 v131, v10, v11
	global_store_dwordx4 v[134:135], v[128:131], off offset:256
	s_nop 1
	v_or_b32_e32 v128, 48, v192
	v_ashrrev_i32_e32 v129, 31, v128
	v_lshlrev_b64 v[128:129], 11, v[128:129]
	v_lshl_add_u64 v[134:135], s[92:93], 0, v[128:129]
	v_lshl_add_u64 v[134:135], v[134:135], 0, s[6:7]
	v_cvt_pk_bf16_f32 v128, v36, v37
	v_cvt_pk_bf16_f32 v129, v38, v39
	v_cvt_pk_bf16_f32 v130, v32, v33
	v_cvt_pk_bf16_f32 v131, v34, v35
	v_lshl_add_u64 v[134:135], v[134:135], 0, v[178:179]
	global_store_dwordx4 v[134:135], v[128:131], off
	s_mov_b64 s[6:7], 0x40000
	s_nop 0
	v_cvt_pk_bf16_f32 v128, v4, v5
	v_cvt_pk_bf16_f32 v129, v6, v7
	v_cvt_pk_bf16_f32 v130, v0, v1
	v_cvt_pk_bf16_f32 v131, v2, v3
	global_store_dwordx4 v[134:135], v[128:131], off offset:256
	v_lshl_add_u64 v[134:135], v[132:133], 0, s[6:7]
	s_mov_b32 s6, 0x40000
	v_add_co_u32_e32 v136, vcc, s6, v132
	v_cvt_pk_bf16_f32 v128, v124, v125
	v_cvt_pk_bf16_f32 v129, v126, v127
	v_cvt_pk_bf16_f32 v130, v120, v121
	v_cvt_pk_bf16_f32 v131, v122, v123
	v_addc_co_u32_e32 v137, vcc, 0, v133, vcc
	global_store_dwordx4 v[136:137], v[128:131], off
	v_add_co_u32_e32 v136, vcc, s83, v132
	s_nop 0
	v_cvt_pk_bf16_f32 v128, v108, v109
	v_cvt_pk_bf16_f32 v129, v110, v111
	v_cvt_pk_bf16_f32 v130, v100, v101
	v_cvt_pk_bf16_f32 v131, v102, v103
	global_store_dwordx4 v[134:135], v[128:131], off offset:256
	s_mov_b64 s[6:7], 0x48000
	v_addc_co_u32_e32 v137, vcc, 0, v133, vcc
	v_cvt_pk_bf16_f32 v128, v116, v117
	v_cvt_pk_bf16_f32 v129, v118, v119
	v_cvt_pk_bf16_f32 v130, v112, v113
	v_cvt_pk_bf16_f32 v131, v114, v115
	v_lshl_add_u64 v[134:135], v[132:133], 0, s[6:7]
	global_store_dwordx4 v[136:137], v[128:131], off
	s_mov_b64 s[6:7], 0x50000
	s_nop 0
	v_cvt_pk_bf16_f32 v128, v92, v93
	v_cvt_pk_bf16_f32 v129, v94, v95
	v_cvt_pk_bf16_f32 v130, v84, v85
	v_cvt_pk_bf16_f32 v131, v86, v87
	global_store_dwordx4 v[134:135], v[128:131], off offset:256
	v_lshl_add_u64 v[134:135], v[132:133], 0, s[6:7]
	s_mov_b32 s6, 0x50000
	v_add_co_u32_e32 v136, vcc, s6, v132
	v_cvt_pk_bf16_f32 v128, v104, v105
	v_cvt_pk_bf16_f32 v129, v106, v107
	v_cvt_pk_bf16_f32 v130, v96, v97
	v_cvt_pk_bf16_f32 v131, v98, v99
	v_addc_co_u32_e32 v137, vcc, 0, v133, vcc
	global_store_dwordx4 v[136:137], v[128:131], off
	s_mov_b64 s[6:7], 0x58000
	s_nop 0
	v_cvt_pk_bf16_f32 v128, v76, v77
	v_cvt_pk_bf16_f32 v129, v78, v79
	v_cvt_pk_bf16_f32 v130, v72, v73
	v_cvt_pk_bf16_f32 v131, v74, v75
	global_store_dwordx4 v[134:135], v[128:131], off offset:256
	v_lshl_add_u64 v[134:135], v[132:133], 0, s[6:7]
	s_mov_b32 s6, 0x58000
	v_add_co_u32_e32 v132, vcc, s6, v132
	v_cvt_pk_bf16_f32 v128, v88, v89
	v_cvt_pk_bf16_f32 v129, v90, v91
	v_cvt_pk_bf16_f32 v130, v80, v81
	v_cvt_pk_bf16_f32 v131, v82, v83
	v_addc_co_u32_e32 v133, vcc, 0, v133, vcc
	global_store_dwordx4 v[132:133], v[128:131], off
	s_nop 1
	v_cvt_pk_bf16_f32 v128, v68, v69
	v_cvt_pk_bf16_f32 v129, v70, v71
	v_cvt_pk_bf16_f32 v130, v64, v65
	v_cvt_pk_bf16_f32 v131, v66, v67
	global_store_dwordx4 v[134:135], v[128:131], off offset:256
